# rownorm scale section: the eight post-gain vector loads issued together behind the wave reduction (was load->wait per group)
# speedup vs baseline: 1.0050x; 1.0017x over previous
; __device__ __forceinline__ float wave_sum(float v) { v += __shfl_xor(v, 32); v += __shfl_xor(v, 16); v += __shfl_xor(v, 8); v += __shfl_xor(v, 4); v += __shfl_xor(v, 2); v += __shfl_xor(v, 1); return v; }
; __device__ __forceinline__ void phase_rownorm(const Ctx& P, LAS unsigned char* lds, const bf16_t* mix, const float* gpost, const float* gnext, int KS, bool glu, bool dry = false) {
;     ...
;         if (mix) {
;             float ss = 0.f;
; #pragma unroll
;             for (int q = 0; q < 8; ++q) ss += sq4(m[q]);
;             ss = wave_sum(ss); const float r = rsqrtf(ss * (1.0f / DM) + EPS);
; #pragma unroll
;             for (int q = 0; q < 8; ++q) { const f32x4 gp = *(const f32x4*)(gpost + q * 256 + lane * 4); x[q] = x[q] + m[q] * r * gp; }
;         }
; #pragma unroll
;         for (int q = 0; q < 8; ++q) *(f32x4*)(Xw + (size_t)row * DM + q * 256 + lane * 4) = x[q];
.LBB0_126:
	s_or_b64 exec, exec, s[46:47]
	v_mul_f32_e32 v126, v123, v123
	v_mul_f32_e32 v185, v119, v119
	v_fmac_f32_e32 v126, v122, v122
	v_fmac_f32_e32 v185, v118, v118
	v_fmac_f32_e32 v126, v124, v124
	v_fmac_f32_e32 v185, v120, v120
	v_fmac_f32_e32 v126, v125, v125
	v_fmac_f32_e32 v185, v121, v121
	v_add_f32_e32 v126, v185, v126
	v_mul_f32_e32 v185, v115, v115
	v_fmac_f32_e32 v185, v114, v114
	v_fmac_f32_e32 v185, v116, v116
	v_fmac_f32_e32 v185, v117, v117
	v_add_f32_e32 v126, v185, v126
	v_mul_f32_e32 v185, v111, v111
	v_mov_b32_e32 v188, v103
	v_mov_b32_e32 v189, v107
	v_fmac_f32_e32 v185, v110, v110
	v_mov_b32_e32 v186, v102
	v_mov_b32_e32 v187, v106
	v_pk_mul_f32 v[188:189], v[188:189], v[188:189]
	v_fmac_f32_e32 v185, v112, v112
	v_pk_fma_f32 v[186:187], v[186:187], v[186:187], v[188:189]
	v_mov_b32_e32 v188, v104
	v_mov_b32_e32 v189, v108
	v_fmac_f32_e32 v185, v113, v113
	v_pk_fma_f32 v[186:187], v[188:189], v[188:189], v[186:187]
	v_mov_b32_e32 v188, v105
	v_mov_b32_e32 v189, v109
	v_add_f32_e32 v126, v185, v126
	v_pk_fma_f32 v[186:187], v[188:189], v[188:189], v[186:187]
	v_mov_b32_e32 v188, v95
	v_add_f32_e32 v126, v187, v126
	v_mov_b32_e32 v189, v99
	v_add_f32_e32 v126, v186, v126
	v_mov_b32_e32 v186, v94
	v_mov_b32_e32 v187, v98
	v_pk_mul_f32 v[188:189], v[188:189], v[188:189]
	s_mov_b32 s3, 0x800000
	v_pk_fma_f32 v[186:187], v[186:187], v[186:187], v[188:189]
	v_mov_b32_e32 v188, v96
	v_mov_b32_e32 v189, v100
	v_pk_fma_f32 v[186:187], v[188:189], v[188:189], v[186:187]
	v_mov_b32_e32 v188, v97
	v_mov_b32_e32 v189, v101
	v_pk_fma_f32 v[186:187], v[188:189], v[188:189], v[186:187]
	s_nop 0
	v_add_f32_e32 v126, v187, v126
	v_add_f32_e32 v126, v186, v126
	global_load_dwordx4 v[186:189], v[70:71], off
	global_load_dwordx4 v[212:215], v[70:71], off offset:1024
	global_load_dwordx4 v[216:219], v[70:71], off offset:2048
	global_load_dwordx4 v[220:223], v[70:71], off offset:3072
	global_load_dwordx4 v[224:227], v[74:75], off
	global_load_dwordx4 v[228:231], v[76:77], off
	global_load_dwordx4 v[232:235], v[78:79], off
	global_load_dwordx4 v[236:239], v[80:81], off
	ds_bpermute_b32 v185, v127, v126
	s_waitcnt lgkmcnt(0)
	v_add_f32_e32 v126, v126, v185
	ds_bpermute_b32 v185, v128, v126
	s_waitcnt lgkmcnt(0)
	v_add_f32_e32 v126, v126, v185
	ds_bpermute_b32 v185, v130, v126
	s_waitcnt lgkmcnt(0)
	v_add_f32_e32 v126, v126, v185
	ds_bpermute_b32 v185, v133, v126
	s_waitcnt lgkmcnt(0)
	v_add_f32_e32 v126, v126, v185
	ds_bpermute_b32 v185, v134, v126
	s_waitcnt lgkmcnt(0)
	v_add_f32_e32 v126, v126, v185
	ds_bpermute_b32 v185, v135, v126
	s_waitcnt lgkmcnt(0)
	v_add_f32_e32 v126, v126, v185
	v_fmamk_f32 v126, v126, 0x3a000000, v163
	v_cmp_gt_f32_e32 vcc, s3, v126
	v_mul_f32_e32 v185, 0x4b800000, v126
	s_nop 0
	v_cndmask_b32_e32 v126, v126, v185, vcc
	v_rsq_f32_e32 v126, v126
	s_nop 0
	v_mul_f32_e32 v185, 0x45800000, v126
	v_cndmask_b32_e32 v126, v126, v185, vcc
	v_pk_mul_f32 v[122:123], v[126:127], v[122:123] op_sel_hi:[0,1]
	v_pk_mul_f32 v[124:125], v[126:127], v[124:125] op_sel_hi:[0,1]
	v_pk_mul_f32 v[118:119], v[126:127], v[118:119] op_sel_hi:[0,1]
	v_pk_mul_f32 v[120:121], v[126:127], v[120:121] op_sel_hi:[0,1]
	v_pk_mul_f32 v[114:115], v[126:127], v[114:115] op_sel_hi:[0,1]
	v_pk_mul_f32 v[116:117], v[126:127], v[116:117] op_sel_hi:[0,1]
	v_pk_mul_f32 v[110:111], v[126:127], v[110:111] op_sel_hi:[0,1]
	v_pk_mul_f32 v[112:113], v[126:127], v[112:113] op_sel_hi:[0,1]
	v_pk_mul_f32 v[106:107], v[126:127], v[106:107] op_sel_hi:[0,1]
	v_pk_mul_f32 v[108:109], v[126:127], v[108:109] op_sel_hi:[0,1]
	v_pk_mul_f32 v[102:103], v[126:127], v[102:103] op_sel_hi:[0,1]
	v_pk_mul_f32 v[104:105], v[126:127], v[104:105] op_sel_hi:[0,1]
	v_pk_mul_f32 v[98:99], v[126:127], v[98:99] op_sel_hi:[0,1]
	v_pk_mul_f32 v[100:101], v[126:127], v[100:101] op_sel_hi:[0,1]
	v_pk_mul_f32 v[94:95], v[126:127], v[94:95] op_sel_hi:[0,1]
	v_pk_mul_f32 v[96:97], v[126:127], v[96:97] op_sel_hi:[0,1]
	s_andn2_b64 vcc, exec, s[38:39]
	s_waitcnt vmcnt(0)
	v_pk_fma_f32 v[62:63], v[188:189], v[124:125], v[62:63]
	v_pk_fma_f32 v[60:61], v[186:187], v[122:123], v[60:61]
	v_mov_b64_e32 v[122:123], v[212:213]
	v_mov_b64_e32 v[124:125], v[214:215]
	s_waitcnt vmcnt(0)
	v_pk_fma_f32 v[58:59], v[124:125], v[120:121], v[58:59]
	v_pk_fma_f32 v[56:57], v[122:123], v[118:119], v[56:57]
	v_mov_b64_e32 v[118:119], v[216:217]
	v_mov_b64_e32 v[120:121], v[218:219]
	s_waitcnt vmcnt(0)
	v_pk_fma_f32 v[54:55], v[120:121], v[116:117], v[54:55]
	v_pk_fma_f32 v[52:53], v[118:119], v[114:115], v[52:53]
	v_mov_b64_e32 v[114:115], v[220:221]
	v_mov_b64_e32 v[116:117], v[222:223]
	s_waitcnt vmcnt(0)
	v_pk_fma_f32 v[50:51], v[116:117], v[112:113], v[50:51]
	v_pk_fma_f32 v[48:49], v[114:115], v[110:111], v[48:49]
	v_mov_b64_e32 v[110:111], v[224:225]
	v_mov_b64_e32 v[112:113], v[226:227]
	s_waitcnt vmcnt(0)
	v_pk_fma_f32 v[46:47], v[112:113], v[108:109], v[46:47]
	v_pk_fma_f32 v[44:45], v[110:111], v[106:107], v[44:45]
	v_mov_b64_e32 v[106:107], v[228:229]
	v_mov_b64_e32 v[108:109], v[230:231]
	s_waitcnt vmcnt(0)
	v_pk_fma_f32 v[42:43], v[108:109], v[104:105], v[42:43]
	v_pk_fma_f32 v[40:41], v[106:107], v[102:103], v[40:41]
	v_mov_b64_e32 v[102:103], v[232:233]
	v_mov_b64_e32 v[104:105], v[234:235]
	s_waitcnt vmcnt(0)
	v_pk_fma_f32 v[38:39], v[104:105], v[100:101], v[38:39]
	v_pk_fma_f32 v[36:37], v[102:103], v[98:99], v[36:37]
	v_mov_b64_e32 v[98:99], v[236:237]
	v_mov_b64_e32 v[100:101], v[238:239]
	s_waitcnt vmcnt(0)
	v_pk_fma_f32 v[34:35], v[100:101], v[96:97], v[34:35]
	v_pk_fma_f32 v[32:33], v[98:99], v[94:95], v[32:33]
	global_store_dwordx4 v[92:93], v[60:63], off offset:-4096
	global_store_dwordx4 v[92:93], v[56:59], off offset:-3072
	global_store_dwordx4 v[92:93], v[52:55], off offset:-2048
	global_store_dwordx4 v[92:93], v[48:51], off offset:-1024
	global_store_dwordx4 v[92:93], v[44:47], off
	global_store_dwordx4 v[92:93], v[40:43], off offset:1024
	global_store_dwordx4 v[92:93], v[36:39], off offset:2048
	global_store_dwordx4 v[92:93], v[32:35], off offset:3072
	s_cbranch_vccnz .LBB0_123
; __device__ __forceinline__ unsigned pk_bf16(float lo, float hi) { unsigned r; asm volatile("v_cvt_pk_bf16_f32 %0, %1, %2" : "=v"(r) : "v"(lo), "v"(hi)); return r; }
; __device__ __forceinline__ float wave_sum(float v) { v += __shfl_xor(v, 32); v += __shfl_xor(v, 16); v += __shfl_xor(v, 8); v += __shfl_xor(v, 4); v += __shfl_xor(v, 2); v += __shfl_xor(v, 1); return v; }
; __device__ __forceinline__ void phase_rownorm(const Ctx& P, LAS unsigned char* lds, const bf16_t* mix, const float* gpost, const float* gnext, int KS, bool glu, bool dry = false) {
;     ...
;         if (gnext) {
;             float ss = 0.f;
; #pragma unroll
;             for (int q = 0; q < 8; ++q) ss += sq4(x[q]);
;             ss = wave_sum(ss); const float r = rsqrtf(ss * (1.0f / DM) + EPS);
; #pragma unroll
;             for (int q = 0; q < 8; ++q) { const f32x4 gn = *(const f32x4*)(gnext + q * 256 + lane * 4); const f32x4 h = x[q] * r * gn;
;                 u32x2 w; w.x = pk_bf16(h[0], h[1]); w.y = pk_bf16(h[2], h[3]);
;                 *(u32x2*)(H + (size_t)row * DM + q * 256 + lane * 4) = w; }
;         }
	v_mul_f32_e32 v94, v61, v61
	v_mul_f32_e32 v95, v57, v57
	v_fmac_f32_e32 v94, v60, v60
	v_fmac_f32_e32 v95, v56, v56
	v_fmac_f32_e32 v94, v62, v62
	v_fmac_f32_e32 v95, v58, v58
	v_fmac_f32_e32 v94, v63, v63
	v_fmac_f32_e32 v95, v59, v59
	v_add_f32_e32 v94, v94, v95
	v_mul_f32_e32 v95, v53, v53
	v_fmac_f32_e32 v95, v52, v52
	v_fmac_f32_e32 v95, v54, v54
	v_fmac_f32_e32 v95, v55, v55
	v_add_f32_e32 v94, v95, v94
	v_mul_f32_e32 v95, v49, v49
	v_fmac_f32_e32 v95, v48, v48
	v_fmac_f32_e32 v95, v50, v50
	v_fmac_f32_e32 v95, v51, v51
	v_mov_b32_e32 v96, v41
	v_mov_b32_e32 v97, v45
	v_add_f32_e32 v98, v95, v94
	v_mov_b32_e32 v94, v40
	v_mov_b32_e32 v95, v44
	v_pk_mul_f32 v[96:97], v[96:97], v[96:97]
	s_nop 0
	v_pk_fma_f32 v[94:95], v[94:95], v[94:95], v[96:97]
	v_mov_b32_e32 v96, v42
	v_mov_b32_e32 v97, v46
	v_pk_fma_f32 v[94:95], v[96:97], v[96:97], v[94:95]
	v_mov_b32_e32 v96, v43
	v_mov_b32_e32 v97, v47
	v_pk_fma_f32 v[94:95], v[96:97], v[96:97], v[94:95]
	v_mov_b32_e32 v96, v33
	v_add_f32_e32 v95, v95, v98
	v_mov_b32_e32 v97, v37
	v_add_f32_e32 v98, v94, v95
	v_mov_b32_e32 v94, v32
	v_mov_b32_e32 v95, v36
	v_pk_mul_f32 v[96:97], v[96:97], v[96:97]
	s_nop 0
	v_pk_fma_f32 v[94:95], v[94:95], v[94:95], v[96:97]
	v_mov_b32_e32 v96, v34
	v_mov_b32_e32 v97, v38
	v_pk_fma_f32 v[94:95], v[96:97], v[96:97], v[94:95]
	v_mov_b32_e32 v96, v35
	v_mov_b32_e32 v97, v39
	v_pk_fma_f32 v[94:95], v[96:97], v[96:97], v[94:95]
	s_nop 0
	v_add_f32_e32 v95, v95, v98
	global_load_dwordx4 v[96:99], v[72:73], off
	v_add_f32_e32 v94, v94, v95
	ds_bpermute_b32 v95, v127, v94
	s_waitcnt lgkmcnt(0)
	v_add_f32_e32 v94, v94, v95
	ds_bpermute_b32 v95, v128, v94
	s_waitcnt lgkmcnt(0)
	v_add_f32_e32 v94, v94, v95
	ds_bpermute_b32 v95, v130, v94
	s_waitcnt lgkmcnt(0)
	v_add_f32_e32 v94, v94, v95
	ds_bpermute_b32 v95, v133, v94
	s_waitcnt lgkmcnt(0)
	v_add_f32_e32 v94, v94, v95
	ds_bpermute_b32 v95, v134, v94
	s_waitcnt lgkmcnt(0)
	v_add_f32_e32 v94, v94, v95
	ds_bpermute_b32 v95, v135, v94
	s_waitcnt lgkmcnt(0)
	v_add_f32_e32 v94, v94, v95
	v_fmamk_f32 v94, v94, 0x3a000000, v163
	v_cmp_gt_f32_e32 vcc, s3, v94
	v_mul_f32_e32 v95, 0x4b800000, v94
	s_nop 0
	v_cndmask_b32_e32 v94, v94, v95, vcc
	v_rsq_f32_e32 v94, v94
	s_nop 0
	v_mul_f32_e32 v95, 0x45800000, v94
	v_cndmask_b32_e32 v94, v94, v95, vcc
	v_pk_mul_f32 v[60:61], v[60:61], v[94:95] op_sel_hi:[1,0]
	v_pk_mul_f32 v[62:63], v[62:63], v[94:95] op_sel_hi:[1,0]
	v_pk_mul_f32 v[56:57], v[56:57], v[94:95] op_sel_hi:[1,0]
	v_pk_mul_f32 v[58:59], v[58:59], v[94:95] op_sel_hi:[1,0]
	v_pk_mul_f32 v[52:53], v[52:53], v[94:95] op_sel_hi:[1,0]
	v_pk_mul_f32 v[54:55], v[54:55], v[94:95] op_sel_hi:[1,0]
	v_pk_mul_f32 v[48:49], v[48:49], v[94:95] op_sel_hi:[1,0]
	v_pk_mul_f32 v[50:51], v[50:51], v[94:95] op_sel_hi:[1,0]
	v_pk_mul_f32 v[44:45], v[44:45], v[94:95] op_sel_hi:[1,0]
	v_pk_mul_f32 v[46:47], v[46:47], v[94:95] op_sel_hi:[1,0]
	v_pk_mul_f32 v[40:41], v[40:41], v[94:95] op_sel_hi:[1,0]
	v_pk_mul_f32 v[42:43], v[42:43], v[94:95] op_sel_hi:[1,0]
	v_pk_mul_f32 v[36:37], v[36:37], v[94:95] op_sel_hi:[1,0]
	v_pk_mul_f32 v[38:39], v[38:39], v[94:95] op_sel_hi:[1,0]
	v_pk_mul_f32 v[32:33], v[32:33], v[94:95] op_sel_hi:[1,0]
	v_pk_mul_f32 v[34:35], v[34:35], v[94:95] op_sel_hi:[1,0]
	s_waitcnt vmcnt(0)
	v_pk_mul_f32 v[60:61], v[96:97], v[60:61]
	v_pk_mul_f32 v[62:63], v[98:99], v[62:63]
	v_cvt_pk_bf16_f32 v60, v60, v61
	s_nop 0
	v_cvt_pk_bf16_f32 v61, v62, v63
	global_store_dwordx2 v[90:91], v[60:61], off
	global_load_dwordx4 v[60:63], v[72:73], off offset:1024
	s_waitcnt vmcnt(0)
	v_pk_mul_f32 v[56:57], v[60:61], v[56:57]
	v_pk_mul_f32 v[58:59], v[62:63], v[58:59]
	v_cvt_pk_bf16_f32 v56, v56, v57
	s_nop 0
	v_cvt_pk_bf16_f32 v57, v58, v59
	global_store_dwordx2 v[90:91], v[56:57], off offset:512
	global_load_dwordx4 v[56:59], v[72:73], off offset:2048
	s_waitcnt vmcnt(0)
	v_pk_mul_f32 v[52:53], v[56:57], v[52:53]
	v_pk_mul_f32 v[54:55], v[58:59], v[54:55]
	v_cvt_pk_bf16_f32 v52, v52, v53
	s_nop 0
	v_cvt_pk_bf16_f32 v53, v54, v55
	global_store_dwordx2 v[90:91], v[52:53], off offset:1024
	global_load_dwordx4 v[52:55], v[72:73], off offset:3072
	s_waitcnt vmcnt(0)
	v_pk_mul_f32 v[48:49], v[48:49], v[52:53]
	v_pk_mul_f32 v[50:51], v[50:51], v[54:55]
	v_cvt_pk_bf16_f32 v48, v48, v49
	s_nop 0
	v_cvt_pk_bf16_f32 v49, v50, v51
	global_store_dwordx2 v[90:91], v[48:49], off offset:1536
	global_load_dwordx4 v[48:51], v[82:83], off
	s_waitcnt vmcnt(0)
	v_pk_mul_f32 v[44:45], v[44:45], v[48:49]
	v_pk_mul_f32 v[46:47], v[46:47], v[50:51]
	v_cvt_pk_bf16_f32 v44, v44, v45
	s_nop 0
	v_cvt_pk_bf16_f32 v45, v46, v47
	global_store_dwordx2 v[90:91], v[44:45], off offset:2048
	global_load_dwordx4 v[44:47], v[84:85], off
	s_waitcnt vmcnt(0)
	v_pk_mul_f32 v[40:41], v[40:41], v[44:45]
	v_pk_mul_f32 v[42:43], v[42:43], v[46:47]
	v_cvt_pk_bf16_f32 v40, v40, v41
	s_nop 0
	v_cvt_pk_bf16_f32 v41, v42, v43
	global_store_dwordx2 v[90:91], v[40:41], off offset:2560
	global_load_dwordx4 v[40:43], v[86:87], off
	s_waitcnt vmcnt(0)
	v_pk_mul_f32 v[36:37], v[36:37], v[40:41]
	v_pk_mul_f32 v[38:39], v[38:39], v[42:43]
	v_cvt_pk_bf16_f32 v36, v36, v37
	s_nop 0
	v_cvt_pk_bf16_f32 v37, v38, v39
	global_store_dwordx2 v[90:91], v[36:37], off offset:3072
	global_load_dwordx4 v[36:39], v[88:89], off
	s_waitcnt vmcnt(0)
	v_pk_mul_f32 v[32:33], v[32:33], v[36:37]
	v_pk_mul_f32 v[34:35], v[34:35], v[38:39]
	v_cvt_pk_bf16_f32 v32, v32, v33
	s_nop 0
	v_cvt_pk_bf16_f32 v33, v34, v35
	global_store_dwordx2 v[90:91], v[32:33], off offset:3584
	s_branch .LBB0_123

; __device__ __forceinline__ float wave_sum(float v) { v += __shfl_xor(v, 32); v += __shfl_xor(v, 16); v += __shfl_xor(v, 8); v += __shfl_xor(v, 4); v += __shfl_xor(v, 2); v += __shfl_xor(v, 1); return v; }
; __device__ __forceinline__ void phase_rownorm(const Ctx& P, LAS unsigned char* lds, const bf16_t* mix, const float* gpost, const float* gnext, int KS, bool glu, bool dry = false) {
;     ...
;         if (mix) {
;             float ss = 0.f;
; #pragma unroll
;             for (int q = 0; q < 8; ++q) ss += sq4(m[q]);
;             ss = wave_sum(ss); const float r = rsqrtf(ss * (1.0f / DM) + EPS);
; #pragma unroll
;             for (int q = 0; q < 8; ++q) { const f32x4 gp = *(const f32x4*)(gpost + q * 256 + lane * 4); x[q] = x[q] + m[q] * r * gp; }
;         }
; #pragma unroll
;         for (int q = 0; q < 8; ++q) *(f32x4*)(Xw + (size_t)row * DM + q * 256 + lane * 4) = x[q];
.LBB0_358:
	s_or_b64 exec, exec, s[38:39]
	v_mul_f32_e32 v126, v123, v123
	v_mul_f32_e32 v185, v119, v119
	v_fmac_f32_e32 v126, v122, v122
	v_fmac_f32_e32 v185, v118, v118
	v_fmac_f32_e32 v126, v124, v124
	v_fmac_f32_e32 v185, v120, v120
	v_fmac_f32_e32 v126, v125, v125
	v_fmac_f32_e32 v185, v121, v121
	v_add_f32_e32 v126, v185, v126
	v_mul_f32_e32 v185, v115, v115
	v_fmac_f32_e32 v185, v114, v114
	v_fmac_f32_e32 v185, v116, v116
	v_fmac_f32_e32 v185, v117, v117
	v_add_f32_e32 v126, v185, v126
	v_mul_f32_e32 v185, v111, v111
	v_mov_b32_e32 v188, v103
	v_mov_b32_e32 v189, v107
	v_fmac_f32_e32 v185, v110, v110
	v_mov_b32_e32 v186, v102
	v_mov_b32_e32 v187, v106
	v_pk_mul_f32 v[188:189], v[188:189], v[188:189]
	v_fmac_f32_e32 v185, v112, v112
	v_pk_fma_f32 v[186:187], v[186:187], v[186:187], v[188:189]
	v_mov_b32_e32 v188, v104
	v_mov_b32_e32 v189, v108
	v_fmac_f32_e32 v185, v113, v113
	v_pk_fma_f32 v[186:187], v[188:189], v[188:189], v[186:187]
	v_mov_b32_e32 v188, v105
	v_mov_b32_e32 v189, v109
	v_add_f32_e32 v126, v185, v126
	v_pk_fma_f32 v[186:187], v[188:189], v[188:189], v[186:187]
	v_mov_b32_e32 v188, v95
	v_add_f32_e32 v126, v187, v126
	v_mov_b32_e32 v189, v99
	v_add_f32_e32 v126, v186, v126
	v_mov_b32_e32 v186, v94
	v_mov_b32_e32 v187, v98
	v_pk_mul_f32 v[188:189], v[188:189], v[188:189]
	s_mov_b32 s3, 0x800000
	v_pk_fma_f32 v[186:187], v[186:187], v[186:187], v[188:189]
	v_mov_b32_e32 v188, v96
	v_mov_b32_e32 v189, v100
	v_pk_fma_f32 v[186:187], v[188:189], v[188:189], v[186:187]
	v_mov_b32_e32 v188, v97
	v_mov_b32_e32 v189, v101
	v_pk_fma_f32 v[186:187], v[188:189], v[188:189], v[186:187]
	s_nop 0
	v_add_f32_e32 v126, v187, v126
	v_add_f32_e32 v126, v186, v126
	global_load_dwordx4 v[186:189], v[70:71], off
	global_load_dwordx4 v[212:215], v[70:71], off offset:1024
	global_load_dwordx4 v[216:219], v[70:71], off offset:2048
	global_load_dwordx4 v[220:223], v[70:71], off offset:3072
	global_load_dwordx4 v[224:227], v[74:75], off
	global_load_dwordx4 v[228:231], v[76:77], off
	global_load_dwordx4 v[232:235], v[78:79], off
	global_load_dwordx4 v[236:239], v[80:81], off
	ds_bpermute_b32 v185, v127, v126
	s_waitcnt lgkmcnt(0)
	v_add_f32_e32 v126, v126, v185
	ds_bpermute_b32 v185, v128, v126
	s_waitcnt lgkmcnt(0)
	v_add_f32_e32 v126, v126, v185
	ds_bpermute_b32 v185, v130, v126
	s_waitcnt lgkmcnt(0)
	v_add_f32_e32 v126, v126, v185
	ds_bpermute_b32 v185, v133, v126
	s_waitcnt lgkmcnt(0)
	v_add_f32_e32 v126, v126, v185
	ds_bpermute_b32 v185, v134, v126
	s_waitcnt lgkmcnt(0)
	v_add_f32_e32 v126, v126, v185
	ds_bpermute_b32 v185, v135, v126
	s_waitcnt lgkmcnt(0)
	v_add_f32_e32 v126, v126, v185
	v_fmamk_f32 v126, v126, 0x3a000000, v163
	v_cmp_gt_f32_e32 vcc, s3, v126
	v_mul_f32_e32 v185, 0x4b800000, v126
	s_nop 0
	v_cndmask_b32_e32 v126, v126, v185, vcc
	v_rsq_f32_e32 v126, v126
	s_nop 0
	v_mul_f32_e32 v185, 0x45800000, v126
	v_cndmask_b32_e32 v126, v126, v185, vcc
	v_pk_mul_f32 v[122:123], v[126:127], v[122:123] op_sel_hi:[0,1]
	v_pk_mul_f32 v[124:125], v[126:127], v[124:125] op_sel_hi:[0,1]
	v_pk_mul_f32 v[118:119], v[126:127], v[118:119] op_sel_hi:[0,1]
	v_pk_mul_f32 v[120:121], v[126:127], v[120:121] op_sel_hi:[0,1]
	v_pk_mul_f32 v[114:115], v[126:127], v[114:115] op_sel_hi:[0,1]
	v_pk_mul_f32 v[116:117], v[126:127], v[116:117] op_sel_hi:[0,1]
	v_pk_mul_f32 v[110:111], v[126:127], v[110:111] op_sel_hi:[0,1]
	v_pk_mul_f32 v[112:113], v[126:127], v[112:113] op_sel_hi:[0,1]
	v_pk_mul_f32 v[106:107], v[126:127], v[106:107] op_sel_hi:[0,1]
	v_pk_mul_f32 v[108:109], v[126:127], v[108:109] op_sel_hi:[0,1]
	v_pk_mul_f32 v[102:103], v[126:127], v[102:103] op_sel_hi:[0,1]
	v_pk_mul_f32 v[104:105], v[126:127], v[104:105] op_sel_hi:[0,1]
	v_pk_mul_f32 v[98:99], v[126:127], v[98:99] op_sel_hi:[0,1]
	v_pk_mul_f32 v[100:101], v[126:127], v[100:101] op_sel_hi:[0,1]
	v_pk_mul_f32 v[94:95], v[126:127], v[94:95] op_sel_hi:[0,1]
	v_pk_mul_f32 v[96:97], v[126:127], v[96:97] op_sel_hi:[0,1]
	s_andn2_b64 vcc, exec, s[44:45]
	s_waitcnt vmcnt(0)
	v_pk_fma_f32 v[62:63], v[188:189], v[124:125], v[62:63]
	v_pk_fma_f32 v[60:61], v[186:187], v[122:123], v[60:61]
	v_mov_b64_e32 v[122:123], v[212:213]
	v_mov_b64_e32 v[124:125], v[214:215]
	s_waitcnt vmcnt(0)
	v_pk_fma_f32 v[58:59], v[124:125], v[120:121], v[58:59]
	v_pk_fma_f32 v[56:57], v[122:123], v[118:119], v[56:57]
	v_mov_b64_e32 v[118:119], v[216:217]
	v_mov_b64_e32 v[120:121], v[218:219]
	s_waitcnt vmcnt(0)
	v_pk_fma_f32 v[54:55], v[120:121], v[116:117], v[54:55]
	v_pk_fma_f32 v[52:53], v[118:119], v[114:115], v[52:53]
	v_mov_b64_e32 v[114:115], v[220:221]
	v_mov_b64_e32 v[116:117], v[222:223]
	s_waitcnt vmcnt(0)
	v_pk_fma_f32 v[50:51], v[116:117], v[112:113], v[50:51]
	v_pk_fma_f32 v[48:49], v[114:115], v[110:111], v[48:49]
	v_mov_b64_e32 v[110:111], v[224:225]
	v_mov_b64_e32 v[112:113], v[226:227]
	s_waitcnt vmcnt(0)
	v_pk_fma_f32 v[46:47], v[112:113], v[108:109], v[46:47]
	v_pk_fma_f32 v[44:45], v[110:111], v[106:107], v[44:45]
	v_mov_b64_e32 v[106:107], v[228:229]
	v_mov_b64_e32 v[108:109], v[230:231]
	s_waitcnt vmcnt(0)
	v_pk_fma_f32 v[42:43], v[108:109], v[104:105], v[42:43]
	v_pk_fma_f32 v[40:41], v[106:107], v[102:103], v[40:41]
	v_mov_b64_e32 v[102:103], v[232:233]
	v_mov_b64_e32 v[104:105], v[234:235]
	s_waitcnt vmcnt(0)
	v_pk_fma_f32 v[38:39], v[104:105], v[100:101], v[38:39]
	v_pk_fma_f32 v[36:37], v[102:103], v[98:99], v[36:37]
	v_mov_b64_e32 v[98:99], v[236:237]
	v_mov_b64_e32 v[100:101], v[238:239]
	s_waitcnt vmcnt(0)
	v_pk_fma_f32 v[34:35], v[100:101], v[96:97], v[34:35]
	v_pk_fma_f32 v[32:33], v[98:99], v[94:95], v[32:33]
	global_store_dwordx4 v[92:93], v[60:63], off offset:-4096
	global_store_dwordx4 v[92:93], v[56:59], off offset:-3072
	global_store_dwordx4 v[92:93], v[52:55], off offset:-2048
	global_store_dwordx4 v[92:93], v[48:51], off offset:-1024
	global_store_dwordx4 v[92:93], v[44:47], off
	global_store_dwordx4 v[92:93], v[40:43], off offset:1024
	global_store_dwordx4 v[92:93], v[36:39], off offset:2048
	global_store_dwordx4 v[92:93], v[32:35], off offset:3072
	s_cbranch_vccnz .LBB0_355
; __device__ __forceinline__ unsigned pk_bf16(float lo, float hi) { unsigned r; asm volatile("v_cvt_pk_bf16_f32 %0, %1, %2" : "=v"(r) : "v"(lo), "v"(hi)); return r; }
; __device__ __forceinline__ float wave_sum(float v) { v += __shfl_xor(v, 32); v += __shfl_xor(v, 16); v += __shfl_xor(v, 8); v += __shfl_xor(v, 4); v += __shfl_xor(v, 2); v += __shfl_xor(v, 1); return v; }
; __device__ __forceinline__ void phase_rownorm(const Ctx& P, LAS unsigned char* lds, const bf16_t* mix, const float* gpost, const float* gnext, int KS, bool glu, bool dry = false) {
;     ...
;         if (gnext) {
;             float ss = 0.f;
; #pragma unroll
;             for (int q = 0; q < 8; ++q) ss += sq4(x[q]);
;             ss = wave_sum(ss); const float r = rsqrtf(ss * (1.0f / DM) + EPS);
; #pragma unroll
;             for (int q = 0; q < 8; ++q) { const f32x4 gn = *(const f32x4*)(gnext + q * 256 + lane * 4); const f32x4 h = x[q] * r * gn;
;                 u32x2 w; w.x = pk_bf16(h[0], h[1]); w.y = pk_bf16(h[2], h[3]);
;                 *(u32x2*)(H + (size_t)row * DM + q * 256 + lane * 4) = w; }
;         }
	v_mul_f32_e32 v94, v61, v61
	v_mul_f32_e32 v95, v57, v57
	v_fmac_f32_e32 v94, v60, v60
	v_fmac_f32_e32 v95, v56, v56
	v_fmac_f32_e32 v94, v62, v62
	v_fmac_f32_e32 v95, v58, v58
	v_fmac_f32_e32 v94, v63, v63
	v_fmac_f32_e32 v95, v59, v59
	v_add_f32_e32 v94, v94, v95
	v_mul_f32_e32 v95, v53, v53
	v_fmac_f32_e32 v95, v52, v52
	v_fmac_f32_e32 v95, v54, v54
	v_fmac_f32_e32 v95, v55, v55
	v_add_f32_e32 v94, v95, v94
	v_mul_f32_e32 v95, v49, v49
	v_fmac_f32_e32 v95, v48, v48
	v_fmac_f32_e32 v95, v50, v50
	v_fmac_f32_e32 v95, v51, v51
	v_mov_b32_e32 v96, v41
	v_mov_b32_e32 v97, v45
	v_add_f32_e32 v98, v95, v94
	v_mov_b32_e32 v94, v40
	v_mov_b32_e32 v95, v44
	v_pk_mul_f32 v[96:97], v[96:97], v[96:97]
	s_nop 0
	v_pk_fma_f32 v[94:95], v[94:95], v[94:95], v[96:97]
	v_mov_b32_e32 v96, v42
	v_mov_b32_e32 v97, v46
	v_pk_fma_f32 v[94:95], v[96:97], v[96:97], v[94:95]
	v_mov_b32_e32 v96, v43
	v_mov_b32_e32 v97, v47
	v_pk_fma_f32 v[94:95], v[96:97], v[96:97], v[94:95]
	v_mov_b32_e32 v96, v33
	v_add_f32_e32 v95, v95, v98
	v_mov_b32_e32 v97, v37
	v_add_f32_e32 v98, v94, v95
	v_mov_b32_e32 v94, v32
	v_mov_b32_e32 v95, v36
	v_pk_mul_f32 v[96:97], v[96:97], v[96:97]
	s_nop 0
	v_pk_fma_f32 v[94:95], v[94:95], v[94:95], v[96:97]
	v_mov_b32_e32 v96, v34
	v_mov_b32_e32 v97, v38
	v_pk_fma_f32 v[94:95], v[96:97], v[96:97], v[94:95]
	v_mov_b32_e32 v96, v35
	v_mov_b32_e32 v97, v39
	v_pk_fma_f32 v[94:95], v[96:97], v[96:97], v[94:95]
	s_nop 0
	v_add_f32_e32 v95, v95, v98
	global_load_dwordx4 v[96:99], v[72:73], off
	v_add_f32_e32 v94, v94, v95
	ds_bpermute_b32 v95, v127, v94
	s_waitcnt lgkmcnt(0)
	v_add_f32_e32 v94, v94, v95
	ds_bpermute_b32 v95, v128, v94
	s_waitcnt lgkmcnt(0)
	v_add_f32_e32 v94, v94, v95
	ds_bpermute_b32 v95, v130, v94
	s_waitcnt lgkmcnt(0)
	v_add_f32_e32 v94, v94, v95
	ds_bpermute_b32 v95, v133, v94
	s_waitcnt lgkmcnt(0)
	v_add_f32_e32 v94, v94, v95
	ds_bpermute_b32 v95, v134, v94
	s_waitcnt lgkmcnt(0)
	v_add_f32_e32 v94, v94, v95
	ds_bpermute_b32 v95, v135, v94
	s_waitcnt lgkmcnt(0)
	v_add_f32_e32 v94, v94, v95
	v_fmamk_f32 v94, v94, 0x3a000000, v163
	v_cmp_gt_f32_e32 vcc, s3, v94
	v_mul_f32_e32 v95, 0x4b800000, v94
	s_nop 0
	v_cndmask_b32_e32 v94, v94, v95, vcc
	v_rsq_f32_e32 v94, v94
	s_nop 0
	v_mul_f32_e32 v95, 0x45800000, v94
	v_cndmask_b32_e32 v94, v94, v95, vcc
	v_pk_mul_f32 v[60:61], v[60:61], v[94:95] op_sel_hi:[1,0]
	v_pk_mul_f32 v[62:63], v[62:63], v[94:95] op_sel_hi:[1,0]
	v_pk_mul_f32 v[56:57], v[56:57], v[94:95] op_sel_hi:[1,0]
	v_pk_mul_f32 v[58:59], v[58:59], v[94:95] op_sel_hi:[1,0]
	v_pk_mul_f32 v[52:53], v[52:53], v[94:95] op_sel_hi:[1,0]
	v_pk_mul_f32 v[54:55], v[54:55], v[94:95] op_sel_hi:[1,0]
	v_pk_mul_f32 v[48:49], v[48:49], v[94:95] op_sel_hi:[1,0]
	v_pk_mul_f32 v[50:51], v[50:51], v[94:95] op_sel_hi:[1,0]
	v_pk_mul_f32 v[44:45], v[44:45], v[94:95] op_sel_hi:[1,0]
	v_pk_mul_f32 v[46:47], v[46:47], v[94:95] op_sel_hi:[1,0]
	v_pk_mul_f32 v[40:41], v[40:41], v[94:95] op_sel_hi:[1,0]
	v_pk_mul_f32 v[42:43], v[42:43], v[94:95] op_sel_hi:[1,0]
	v_pk_mul_f32 v[36:37], v[36:37], v[94:95] op_sel_hi:[1,0]
	v_pk_mul_f32 v[38:39], v[38:39], v[94:95] op_sel_hi:[1,0]
	v_pk_mul_f32 v[32:33], v[32:33], v[94:95] op_sel_hi:[1,0]
	v_pk_mul_f32 v[34:35], v[34:35], v[94:95] op_sel_hi:[1,0]
	s_waitcnt vmcnt(0)
	v_pk_mul_f32 v[60:61], v[96:97], v[60:61]
	v_pk_mul_f32 v[62:63], v[98:99], v[62:63]
	v_cvt_pk_bf16_f32 v60, v60, v61
	s_nop 0
	v_cvt_pk_bf16_f32 v61, v62, v63
	global_store_dwordx2 v[90:91], v[60:61], off
	global_load_dwordx4 v[60:63], v[72:73], off offset:1024
	s_waitcnt vmcnt(0)
	v_pk_mul_f32 v[56:57], v[60:61], v[56:57]
	v_pk_mul_f32 v[58:59], v[62:63], v[58:59]
	v_cvt_pk_bf16_f32 v56, v56, v57
	s_nop 0
	v_cvt_pk_bf16_f32 v57, v58, v59
	global_store_dwordx2 v[90:91], v[56:57], off offset:512
	global_load_dwordx4 v[56:59], v[72:73], off offset:2048
	s_waitcnt vmcnt(0)
	v_pk_mul_f32 v[52:53], v[56:57], v[52:53]
	v_pk_mul_f32 v[54:55], v[58:59], v[54:55]
	v_cvt_pk_bf16_f32 v52, v52, v53
	s_nop 0
	v_cvt_pk_bf16_f32 v53, v54, v55
	global_store_dwordx2 v[90:91], v[52:53], off offset:1024
	global_load_dwordx4 v[52:55], v[72:73], off offset:3072
	s_waitcnt vmcnt(0)
	v_pk_mul_f32 v[48:49], v[48:49], v[52:53]
	v_pk_mul_f32 v[50:51], v[50:51], v[54:55]
	v_cvt_pk_bf16_f32 v48, v48, v49
	s_nop 0
	v_cvt_pk_bf16_f32 v49, v50, v51
	global_store_dwordx2 v[90:91], v[48:49], off offset:1536
	global_load_dwordx4 v[48:51], v[82:83], off
	s_waitcnt vmcnt(0)
	v_pk_mul_f32 v[44:45], v[44:45], v[48:49]
	v_pk_mul_f32 v[46:47], v[46:47], v[50:51]
	v_cvt_pk_bf16_f32 v44, v44, v45
	s_nop 0
	v_cvt_pk_bf16_f32 v45, v46, v47
	global_store_dwordx2 v[90:91], v[44:45], off offset:2048
	global_load_dwordx4 v[44:47], v[84:85], off
	s_waitcnt vmcnt(0)
	v_pk_mul_f32 v[40:41], v[40:41], v[44:45]
	v_pk_mul_f32 v[42:43], v[42:43], v[46:47]
	v_cvt_pk_bf16_f32 v40, v40, v41
	s_nop 0
	v_cvt_pk_bf16_f32 v41, v42, v43
	global_store_dwordx2 v[90:91], v[40:41], off offset:2560
	global_load_dwordx4 v[40:43], v[86:87], off
	s_waitcnt vmcnt(0)
	v_pk_mul_f32 v[36:37], v[36:37], v[40:41]
	v_pk_mul_f32 v[38:39], v[38:39], v[42:43]
	v_cvt_pk_bf16_f32 v36, v36, v37
	s_nop 0
	v_cvt_pk_bf16_f32 v37, v38, v39
	global_store_dwordx2 v[90:91], v[36:37], off offset:3072
	global_load_dwordx4 v[36:39], v[88:89], off
	s_waitcnt vmcnt(0)
	v_pk_mul_f32 v[32:33], v[32:33], v[36:37]
	v_pk_mul_f32 v[34:35], v[34:35], v[38:39]
	v_cvt_pk_bf16_f32 v32, v32, v33
	s_nop 0
	v_cvt_pk_bf16_f32 v33, v34, v35
	global_store_dwordx2 v[90:91], v[32:33], off offset:3584
	s_branch .LBB0_355
